# ATTN ping-pong v6 + LOAD segment issues its LDS reads right behind the head barrier, the K/V LDS-DMA of tile kt+2 and the mask load go out behind them
# speedup vs baseline: 1.0203x; 1.0072x over previous
.Lpp_hb:
	s_waitcnt lgkmcnt(0)
	s_barrier
	s_cmp_gt_u32 s35, s28
	s_cbranch_scc1 .Lpp_skip
	v_add_u32_e32 v149, s5, v140
	v_add_u32_e32 v150, s5, v141
	v_add_u32_sdwa v230, v4, s25 dst_sel:DWORD dst_unused:UNUSED_PAD src0_sel:BYTE_0 src1_sel:DWORD
	v_add_u32_sdwa v231, v4, s25 dst_sel:DWORD dst_unused:UNUSED_PAD src0_sel:BYTE_1 src1_sel:DWORD
	v_add_u32_sdwa v232, v4, s25 dst_sel:DWORD dst_unused:UNUSED_PAD src0_sel:BYTE_2 src1_sel:DWORD
	v_add_u32_sdwa v233, v4, s25 dst_sel:DWORD dst_unused:UNUSED_PAD src0_sel:BYTE_3 src1_sel:DWORD
	v_add_u32_sdwa v234, v3, s25 dst_sel:DWORD dst_unused:UNUSED_PAD src0_sel:BYTE_0 src1_sel:DWORD
	v_add_u32_sdwa v235, v3, s25 dst_sel:DWORD dst_unused:UNUSED_PAD src0_sel:BYTE_1 src1_sel:DWORD
	v_add_u32_sdwa v236, v3, s25 dst_sel:DWORD dst_unused:UNUSED_PAD src0_sel:BYTE_2 src1_sel:DWORD
	v_add_u32_sdwa v237, v3, s25 dst_sel:DWORD dst_unused:UNUSED_PAD src0_sel:BYTE_3 src1_sel:DWORD
	ds_read_b128 v[66:69], v230
	ds_read_b128 v[70:73], v231
	ds_read_b128 v[74:77], v232
	ds_read_b128 v[78:81], v233
	ds_read_b128 v[182:185], v149
	ds_read_b128 v[186:189], v149 offset:2048
	ds_read_b128 v[190:193], v149 offset:4096
	ds_read_b128 v[194:197], v149 offset:6144
	ds_read_b128 v[82:85], v234
	ds_read_b128 v[86:89], v235
	ds_read_b128 v[90:93], v236
	ds_read_b128 v[94:97], v237
	s_waitcnt lgkmcnt(8)
	ds_read_b128 v[198:201], v149 offset:512
	ds_read_b128 v[202:205], v149 offset:2560
	ds_read_b128 v[206:209], v149 offset:4608
	ds_read_b128 v[210:213], v149 offset:6656
	s_waitcnt lgkmcnt(8)
	ds_read_b64_tr_b16 v[152:153], v150
	ds_read_b64_tr_b16 v[154:155], v150 offset:512
	ds_read_b64_tr_b16 v[156:157], v150 offset:1024
	ds_read_b64_tr_b16 v[158:159], v150 offset:1536
	s_waitcnt lgkmcnt(8)
	ds_read_b64_tr_b16 v[160:161], v150 offset:2048
	ds_read_b64_tr_b16 v[162:163], v150 offset:2560
	ds_read_b64_tr_b16 v[164:165], v150 offset:3072
	ds_read_b64_tr_b16 v[166:167], v150 offset:3584
	s_waitcnt lgkmcnt(8)
	ds_read_b64_tr_b16 v[168:169], v150 offset:4096
	ds_read_b64_tr_b16 v[170:171], v150 offset:4608
	ds_read_b64_tr_b16 v[172:173], v150 offset:5120
	ds_read_b64_tr_b16 v[174:175], v150 offset:5632
	s_waitcnt lgkmcnt(8)
	ds_read_b64_tr_b16 v[214:215], v150 offset:6144
	ds_read_b64_tr_b16 v[216:217], v150 offset:6656
	ds_read_b64_tr_b16 v[218:219], v150 offset:7168
	ds_read_b64_tr_b16 v[220:221], v150 offset:7680
	s_add_i32 s7, s6, 0x6000
	s_mov_b32 m0, s6
	global_load_lds_dwordx4 v[6:7], off
	s_mov_b32 m0, s7
	global_load_lds_dwordx4 v[8:9], off
	s_add_i32 s6, s15, -1
	s_cmp_lt_u32 s35, 63
	s_cselect_b32 s10, s6, 63
	s_lshl_b64 s[6:7], s[10:11], 15
	v_lshl_add_u64 v[6:7], v[136:137], 0, s[6:7]
	global_load_dwordx2 v[138:139], v[6:7], off
	s_waitcnt lgkmcnt(0)
	s_barrier
	v_mfma_f32_32x32x16_bf16 v[66:81], v[182:185], v[110:113], v[66:81]
	v_mfma_f32_32x32x16_bf16 v[66:81], v[186:189], v[98:101], v[66:81]
	v_mfma_f32_32x32x16_bf16 v[66:81], v[190:193], v[102:105], v[66:81]
	v_mfma_f32_32x32x16_bf16 v[66:81], v[194:197], v[106:109], v[66:81]
	s_cmp_lt_u32 s33, s14
	s_cbranch_scc0 .Lpp_bias
	v_mfma_f32_32x32x16_bf16 v[82:97], v[198:201], v[110:113], v[82:97]
	s_add_i32 s5, s34, 1
	s_cmp_lg_u32 s34, 2
	s_cselect_b32 s34, s5, 0
	v_mfma_f32_32x32x16_bf16 v[82:97], v[202:205], v[98:101], v[82:97]
	s_addk_i32 s31, 0xff00
	s_add_i32 s15, s15, 1
	s_add_i32 s5, s30, s31
	v_mfma_f32_32x32x16_bf16 v[82:97], v[206:209], v[102:105], v[82:97]
	s_add_i32 s33, s33, 64
	s_cmp_eq_u32 s5, 0
	s_cselect_b32 s37, 1, 0
	v_exp_f32_e32 v66, v66
	v_exp_f32_e32 v67, v67
	v_exp_f32_e32 v68, v68
	v_mfma_f32_32x32x16_bf16 v[82:97], v[210:213], v[106:109], v[82:97]
	v_exp_f32_e32 v69, v69
	v_exp_f32_e32 v70, v70
	v_exp_f32_e32 v71, v71
	v_exp_f32_e32 v72, v72
	v_exp_f32_e32 v73, v73
	v_cvt_pk_bf16_f32 v4, v66, v67
	v_cvt_pk_bf16_f32 v5, v68, v69
	v_cvt_pk_bf16_f32 v6, v70, v71
	v_cvt_pk_bf16_f32 v7, v72, v73
	v_exp_f32_e32 v74, v74
	v_exp_f32_e32 v75, v75
	v_mfma_f32_32x32x16_bf16 v[34:49], v[4:7], v[152:155], v[34:49]
	v_exp_f32_e32 v76, v76
	v_exp_f32_e32 v77, v77
	v_exp_f32_e32 v78, v78
	v_mfma_f32_32x32x16_bf16 v[18:33], v[4:7], v[168:171], v[18:33]
	v_exp_f32_e32 v79, v79
	v_exp_f32_e32 v80, v80
	v_exp_f32_e32 v81, v81
	v_mfma_f32_32x32x16_bf16 v[50:65], v[4:7], v[226:229], v[50:65]
	v_cvt_pk_bf16_f32 v8, v74, v75
	v_cvt_pk_bf16_f32 v9, v76, v77
	v_cvt_pk_bf16_f32 v10, v78, v79
	v_cvt_pk_bf16_f32 v11, v80, v81
	v_exp_f32_e32 v82, v82
	v_exp_f32_e32 v83, v83
	v_mfma_f32_32x32x16_bf16 v[34:49], v[8:11], v[156:159], v[34:49]
	v_exp_f32_e32 v84, v84
	v_exp_f32_e32 v85, v85
	v_exp_f32_e32 v86, v86
	v_mfma_f32_32x32x16_bf16 v[18:33], v[8:11], v[172:175], v[18:33]
	v_exp_f32_e32 v87, v87
	v_exp_f32_e32 v88, v88
	v_exp_f32_e32 v89, v89
	v_mfma_f32_32x32x16_bf16 v[50:65], v[8:11], v[226:229], v[50:65]
	v_cvt_pk_bf16_f32 v12, v82, v83
	v_cvt_pk_bf16_f32 v13, v84, v85
	v_cvt_pk_bf16_f32 v14, v86, v87
	v_cvt_pk_bf16_f32 v15, v88, v89
	v_exp_f32_e32 v90, v90
	v_exp_f32_e32 v91, v91
	v_mfma_f32_32x32x16_bf16 v[34:49], v[12:15], v[160:163], v[34:49]
	v_exp_f32_e32 v92, v92
	v_exp_f32_e32 v93, v93
	v_exp_f32_e32 v94, v94
	s_add_i32 s35, s15, -2
	s_lshl_b32 s5, s34, 13
	s_cmp_lt_u32 s15, s27
	s_cselect_b32 s10, s15, s29
	v_mfma_f32_32x32x16_bf16 v[18:33], v[12:15], v[214:217], v[18:33]
	v_exp_f32_e32 v95, v95
	v_exp_f32_e32 v96, v96
	v_exp_f32_e32 v97, v97
	s_lshl_b64 s[6:7], s[10:11], 16
	s_waitcnt vmcnt(0)
	v_mfma_f32_32x32x16_bf16 v[50:65], v[12:15], v[226:229], v[50:65]
	v_cvt_pk_bf16_f32 v222, v90, v91
	v_cvt_pk_bf16_f32 v223, v92, v93
	v_cvt_pk_bf16_f32 v224, v94, v95
	v_cvt_pk_bf16_f32 v225, v96, v97
	v_lshl_add_u64 v[6:7], v[116:117], 0, s[6:7]
	v_lshl_add_u64 v[8:9], v[118:119], 0, s[6:7]
	v_mfma_f32_32x32x16_bf16 v[34:49], v[222:225], v[164:167], v[34:49]
	v_lshrrev_b32_e32 v3, v1, v138
	s_add_i32 s6, s5, 0xffffe000
	v_lshlrev_b32_e32 v3, 4, v3
	s_cmp_lg_u32 s34, 0
	v_and_b32_e32 v4, 0xf0f0f0f0, v3
	v_mfma_f32_32x32x16_bf16 v[18:33], v[222:225], v[218:221], v[18:33]
	v_lshrrev_b32_e32 v3, v1, v139
	s_cselect_b32 s6, s6, 0x4000
	v_lshlrev_b32_e32 v3, 4, v3
	s_add_i32 s6, s20, s6
	v_and_b32_e32 v3, 0xf0f0f0f0, v3
	v_mfma_f32_32x32x16_bf16 v[50:65], v[222:225], v[226:229], v[50:65]
	s_cmp_lg_u32 s37, 0
	s_cbranch_scc1 .LBB0_946
	s_branch .Lpp_hb

.Lpp_skip:
	s_add_i32 s7, s6, 0x6000
	s_mov_b32 m0, s6
	global_load_lds_dwordx4 v[6:7], off
	s_mov_b32 m0, s7
	global_load_lds_dwordx4 v[8:9], off
	s_add_i32 s6, s15, -1
	s_cmp_lt_u32 s35, 63
	s_cselect_b32 s10, s6, 63
	s_lshl_b64 s[6:7], s[10:11], 15
	v_lshl_add_u64 v[6:7], v[136:137], 0, s[6:7]
	global_load_dwordx2 v[138:139], v[6:7], off
	s_waitcnt lgkmcnt(0)
	s_barrier
	s_branch .LBB0_954
